# RES1 epilogue: second row-group batch's residual tiles requested together with the first (idle registers), one exposed memory round trip per unit instead of two
# baseline (speedup 1.0000x reference)
; __device__ __forceinline__ u32x4 pack8(const float (&f)[8]) { u32x4 w; w.x = pk2(f[0], f[1]); w.y = pk2(f[2], f[3]); w.z = pk2(f[4], f[5]); w.w = pk2(f[6], f[7]); return w; }
;     __device__ __forceinline__ void load(Pre& p, const pg8::Unit& u, int ai, int m, int wr, int wc, int fr, int fq) const {
;         const int row = u.pm * 256 + ai * 128 + wr * 64 + m * 16 + fr;
;         if (MODE == EM_PROJ || MODE == EM_GATES) p.rs = ((const float*)(ws + WS_RINV0))[row];
;         if (MODE == EM_RES2) p.rs = ((const float*)(ws + WS_SS1))[row];
; #pragma unroll
;         for (int bj = 0; bj < 2; ++bj) {
;             const int ct = bj * 128 + wc * 32 + fq * 8; const size_t o = (size_t)row * 1024 + u.pn * 256 + ct;
;             if (MODE == EM_MERGE) { const unsigned char* g8 = ws + WS_G8 + (size_t)row * 2048 + u.pn * 256 + ct; const u32x2 ga = *(const u32x2*)g8, gc = *(const u32x2*)(g8 + 1024);
;                 p.a[bj] = (u32x4){ga.x, ga.y, gc.x, gc.y}; p.b[bj] = *(const u32x4*)((const bf16_t*)(ws + WS_YHG) + o); }
;             if (MODE == EM_RES1) p.a[bj] = *(const u32x4*)((const bf16_t*)(ws + WS_XB) + o);
;     __device__ __forceinline__ float compute(const Pre& p, f32x4 (&acc)[2][2][4][2], const f32x4 (&cv)[2][2], const pg8::Unit& u, int ai, int m, int wr, int wc, int fr, int fq) const {
;     ...
;             } else if (MODE == EM_RES1) {
;                 const size_t o = (size_t)row * 1024 + u.pn * 256 + ct;
;                 float w[8], xr[8]; unpack8(p.a[bj], xr);
; #pragma unroll
;                 for (int j = 0; j < 8; ++j) { w[j] = v[j] + xr[j]; ssq += w[j] * w[j]; }
;                 pk[bj] = pack8(w); (void)o;
.LBB0_1254:
	s_mov_b32 s72, 0x40000
	s_mov_b32 s73, 0
	s_lshl_b32 s23, s30, 8
	s_add_i32 s34, s23, s3
	s_lshl_b32 s30, s31, 8
	v_or_b32_e32 v170, s34, v176
	s_ashr_i32 s31, s30, 31
	s_lshl_b64 s[30:31], s[30:31], 1
	v_ashrrev_i32_e32 v171, 31, v170
	v_lshl_add_u64 v[172:173], v[160:161], 0, s[30:31]
	v_lshlrev_b64 v[128:129], 11, v[170:171]
	v_lshl_add_u64 v[130:131], v[172:173], 0, v[128:129]
	v_lshl_add_u64 v[174:175], v[158:159], 0, s[30:31]
	global_load_dwordx4 v[184:187], v[130:131], off
	v_lshl_add_u64 v[240:241], v[130:131], 0, s[72:73]
	global_load_dwordx4 v[208:211], v[240:241], off
	v_lshl_add_u64 v[128:129], v[174:175], 0, v[128:129]
	v_add_co_u32_e32 v128, vcc, 0x3400000, v128
	v_or_b32_e32 v132, 48, v170
	s_nop 0
	v_addc_co_u32_e32 v129, vcc, 0, v129, vcc
	global_load_dwordx4 v[188:191], v[128:129], off offset:256
	v_lshl_add_u64 v[240:241], v[128:129], 0, s[72:73]
	global_load_dwordx4 v[212:215], v[240:241], off offset:256
	v_or_b32_e32 v128, 16, v170
	v_ashrrev_i32_e32 v129, 31, v128
	v_lshlrev_b64 v[128:129], 11, v[128:129]
	v_lshl_add_u64 v[134:135], v[172:173], 0, v[128:129]
	v_lshl_add_u64 v[128:129], v[174:175], 0, v[128:129]
	v_add_co_u32_e32 v128, vcc, 0x3400000, v128
	v_or_b32_e32 v130, 32, v170
	s_nop 0
	v_addc_co_u32_e32 v129, vcc, 0, v129, vcc
	global_load_dwordx4 v[192:195], v[134:135], off
	v_lshl_add_u64 v[240:241], v[134:135], 0, s[72:73]
	global_load_dwordx4 v[216:219], v[240:241], off
	global_load_dwordx4 v[196:199], v[128:129], off offset:256
	v_lshl_add_u64 v[240:241], v[128:129], 0, s[72:73]
	global_load_dwordx4 v[220:223], v[240:241], off offset:256
	v_ashrrev_i32_e32 v131, 31, v130
	v_lshlrev_b64 v[130:131], 11, v[130:131]
	v_lshl_add_u64 v[136:137], v[172:173], 0, v[130:131]
	v_lshl_add_u64 v[130:131], v[174:175], 0, v[130:131]
	v_add_co_u32_e32 v130, vcc, 0x3400000, v130
	v_ashrrev_i32_e32 v133, 31, v132
	s_nop 0
	v_addc_co_u32_e32 v131, vcc, 0, v131, vcc
	global_load_dwordx4 v[140:143], v[136:137], off
	v_lshl_add_u64 v[240:241], v[136:137], 0, s[72:73]
	global_load_dwordx4 v[224:227], v[240:241], off
	s_nop 0
	global_load_dwordx4 v[136:139], v[130:131], off offset:256
	v_lshl_add_u64 v[240:241], v[130:131], 0, s[72:73]
	global_load_dwordx4 v[228:231], v[240:241], off offset:256
	v_lshlrev_b64 v[132:133], 11, v[132:133]
	v_lshl_add_u64 v[200:201], v[172:173], 0, v[132:133]
	v_lshl_add_u64 v[132:133], v[174:175], 0, v[132:133]
	v_add_co_u32_e32 v128, vcc, 0x3400000, v132
	s_ashr_i32 s35, s34, 31
	s_nop 0
	v_addc_co_u32_e32 v129, vcc, 0, v133, vcc
	global_load_dwordx4 v[132:135], v[200:201], off
	v_lshl_add_u64 v[240:241], v[200:201], 0, s[72:73]
	global_load_dwordx4 v[232:235], v[240:241], off
	s_nop 0
	global_load_dwordx4 v[128:131], v[128:129], off offset:256
	v_lshl_add_u64 v[240:241], v[128:129], 0, s[72:73]
	global_load_dwordx4 v[236:239], v[240:241], off offset:256
	s_lshl_b64 s[36:37], s[34:35], 11
	s_add_u32 s23, s58, s36
	s_addc_u32 s25, s59, s37
	s_add_u32 s36, s23, s30
	s_addc_u32 s37, s25, s31
	s_waitcnt vmcnt(0)
	v_lshlrev_b32_e32 v200, 16, v184
	v_and_b32_e32 v201, 0xffff0000, v184
	v_lshlrev_b32_e32 v184, 16, v185
	v_and_b32_e32 v185, 0xffff0000, v185
	v_pk_add_f32 v[124:125], v[124:125], v[200:201]
	v_lshlrev_b32_e32 v202, 16, v186
	v_and_b32_e32 v203, 0xffff0000, v186
	v_pk_add_f32 v[126:127], v[126:127], v[184:185]
	v_pk_mul_f32 v[200:201], v[124:125], v[124:125]
	v_pk_add_f32 v[184:185], v[120:121], v[202:203]
	v_pk_mul_f32 v[202:203], v[126:127], v[126:127]
	v_cvt_pk_bf16_f32 v120, v124, v125
	v_lshlrev_b32_e32 v124, 16, v188
	v_and_b32_e32 v125, 0xffff0000, v188
	v_add_f32_e32 v188, v200, v201
	v_add_f32_e32 v188, v202, v188
	v_lshlrev_b32_e32 v186, 16, v187
	v_and_b32_e32 v187, 0xffff0000, v187
	v_pk_mul_f32 v[204:205], v[184:185], v[184:185]
	v_add_f32_e32 v188, v203, v188
	v_pk_add_f32 v[186:187], v[122:123], v[186:187]
	v_add_f32_e32 v188, v204, v188
	v_pk_mul_f32 v[206:207], v[186:187], v[186:187]
	v_add_f32_e32 v188, v205, v188
	v_cvt_pk_bf16_f32 v122, v184, v185
	v_lshlrev_b32_e32 v184, 16, v190
	v_and_b32_e32 v185, 0xffff0000, v190
	v_pk_add_f32 v[116:117], v[116:117], v[124:125]
	v_add_f32_e32 v188, v206, v188
	v_cvt_pk_bf16_f32 v121, v126, v127
	v_lshlrev_b32_e32 v126, 16, v189
	v_and_b32_e32 v127, 0xffff0000, v189
	v_pk_add_f32 v[124:125], v[112:113], v[184:185]
	v_pk_mul_f32 v[112:113], v[116:117], v[116:117]
	v_add_f32_e32 v188, v207, v188
	v_cvt_pk_bf16_f32 v123, v186, v187
	v_lshlrev_b32_e32 v186, 16, v191
	v_and_b32_e32 v187, 0xffff0000, v191
	v_pk_add_f32 v[118:119], v[118:119], v[126:127]
	v_add_f32_e32 v112, v112, v188
	v_pk_add_f32 v[126:127], v[114:115], v[186:187]
	v_pk_mul_f32 v[114:115], v[118:119], v[118:119]
	v_add_f32_e32 v112, v113, v112
	v_add_f32_e32 v112, v114, v112
	v_pk_mul_f32 v[184:185], v[124:125], v[124:125]
	v_add_f32_e32 v112, v115, v112
	v_add_f32_e32 v112, v184, v112
	v_pk_mul_f32 v[186:187], v[126:127], v[126:127]
	v_add_f32_e32 v112, v185, v112
	v_add_f32_e32 v112, v186, v112
	v_add_f32_e32 v184, v187, v112
	v_cvt_pk_bf16_f32 v112, v116, v117
	v_cvt_pk_bf16_f32 v113, v118, v119
	v_cvt_pk_bf16_f32 v114, v124, v125
	v_cvt_pk_bf16_f32 v115, v126, v127
	ds_write_b128 v181, v[120:123]
	ds_write_b128 v181, v[112:115] offset:256
	s_waitcnt lgkmcnt(0)
	s_barrier
;     __device__ __forceinline__ void stage512(const u32x4 a, const u32x4 b, unsigned char* g0, size_t ldb, int wr, int wc, int fr, int fq) const {
;         LAS unsigned char* sb = lds + LDS_STG + wr * 8448;
;     __device__ __forceinline__ float compute(const Pre& p, f32x4 (&acc)[2][2][4][2], const f32x4 (&cv)[2][2], const pg8::Unit& u, int ai, int m, int wr, int wc, int fr, int fq) const {
;     ...
;             } else if (MODE == EM_RES1) {
;                 const size_t o = (size_t)row * 1024 + u.pn * 256 + ct;
;                 float w[8], xr[8]; unpack8(p.a[bj], xr);
; #pragma unroll
;                 for (int j = 0; j < 8; ++j) { w[j] = v[j] + xr[j]; ssq += w[j] * w[j]; }
;                 pk[bj] = pack8(w); (void)o;
;             } else if (MODE == EM_RES2) {
;                 const size_t o = (size_t)row * 1024 + u.pn * 256 + ct;
;                 float pe[8], h1[8]; unpack8(p.a[bj], pe); unpack8(p.b[bj], h1);
;                 float w[8];
; #pragma unroll
;                 for (int j = 0; j < 8; ++j) { w[j] = h1[j] + pe[j] * sigmoidf_(v[j] * rs); ssq += w[j] * w[j]; }
;                 acc[ai][bj][m][0] = (f32x4){w[0], w[1], w[2], w[3]}; acc[ai][bj][m][1] = (f32x4){w[4], w[5], w[6], w[7]};
;                 (void)o;
;             } else if (MODE == EM_S5A) {
;                 float* e = (float*)(ws + WS_E) + (size_t)row * 128 + ct;
;                 *(f32x4*)e = (f32x4){v[0], v[1], v[2], v[3]}; *(f32x4*)(e + 4) = (f32x4){v[4], v[5], v[6], v[7]};
;             } else if (MODE == EM_S5C) {
;                 const int g = u.pn, cr = row - g * 2048; const int tok = cr * 16 + (ct >> 4);
;                 float w[8];
; #pragma unroll
;                 for (int j = 0; j < 8; ++j) w[j] = gelu_tanh(v[j]);
;                 *(u32x4*)((bf16_t*)(ws + WS_YSA) + (size_t)tok * 512 + g * 16 + (ct & 15)) = pack8(w);
;             }
;         }
;         if (MODE == EM_PLAIN) stage512(pk[0], pk[1], (unsigned char*)O + (trow * ldc + u.pn * 256) * 2, (size_t)ldc * 2, wr, wc, fr, fq);
;         if (MODE == EM_MERGE) stage512(pk[0], pk[1], ws + WS_MRG + (trow * 1024 + u.pn * 256) * 2, 2048, wr, wc, fr, fq);
;         if (MODE == EM_RES1) stage512(pk[0], pk[1], ws + WS_H1B + (trow * 1024 + u.pn * 256) * 2, 2048, wr, wc, fr, fq);
;         if (MODE == EM_RES1 || MODE == EM_RES2) { ssq += __shfl_xor(ssq, 16); ssq += __shfl_xor(ssq, 32); }
	ds_read_b128 v[112:115], v182
	ds_read_b128 v[116:119], v182 offset:4224
	v_lshl_add_u64 v[120:121], s[36:37], 0, v[152:153]
	v_lshl_add_u64 v[122:123], v[120:121], 0, v[154:155]
	s_or_b32 s36, s34, 16
	s_waitcnt lgkmcnt(1)
	global_store_dwordx4 v[122:123], v[112:115], off
	s_ashr_i32 s37, s36, 31
	s_lshl_b64 s[36:37], s[36:37], 11
	v_and_b32_e32 v115, 64, v183
	v_xor_b32_e32 v114, 16, v183
	v_add_u32_e32 v115, 64, v115
	v_cmp_lt_i32_e32 vcc, v114, v115
	v_lshl_add_u64 v[112:113], v[120:121], 0, v[156:157]
	s_waitcnt lgkmcnt(0)
	global_store_dwordx4 v[112:113], v[116:119], off
	v_cndmask_b32_e32 v114, v183, v114, vcc
	v_lshlrev_b32_e32 v114, 2, v114
	ds_bpermute_b32 v120, v114, v184
	v_lshlrev_b32_e32 v116, 16, v192
	v_and_b32_e32 v117, 0xffff0000, v192
	v_pk_add_f32 v[108:109], v[108:109], v[116:117]
	v_lshlrev_b32_e32 v118, 16, v193
	v_and_b32_e32 v119, 0xffff0000, v193
	v_pk_mul_f32 v[116:117], v[108:109], v[108:109]
	v_pk_add_f32 v[110:111], v[110:111], v[118:119]
	s_waitcnt lgkmcnt(0)
	v_add_f32_e32 v112, v184, v120
	v_pk_mul_f32 v[118:119], v[110:111], v[110:111]
	v_lshlrev_b32_e32 v120, 16, v194
	v_and_b32_e32 v121, 0xffff0000, v194
	v_add_f32_e32 v116, v116, v117
	v_pk_add_f32 v[120:121], v[104:105], v[120:121]
	v_add_f32_e32 v116, v118, v116
	v_pk_mul_f32 v[122:123], v[120:121], v[120:121]
	v_lshlrev_b32_e32 v104, 16, v195
	v_and_b32_e32 v105, 0xffff0000, v195
	v_add_f32_e32 v116, v119, v116
	v_pk_add_f32 v[124:125], v[106:107], v[104:105]
	v_add_f32_e32 v116, v122, v116
	v_pk_mul_f32 v[126:127], v[124:125], v[124:125]
	v_cvt_pk_bf16_f32 v104, v108, v109
	v_lshlrev_b32_e32 v108, 16, v196
	v_and_b32_e32 v109, 0xffff0000, v196
	v_add_f32_e32 v116, v123, v116
	v_pk_add_f32 v[100:101], v[100:101], v[108:109]
	v_add_f32_e32 v116, v126, v116
	v_cvt_pk_bf16_f32 v105, v110, v111
	v_pk_mul_f32 v[108:109], v[100:101], v[100:101]
	v_lshlrev_b32_e32 v110, 16, v197
	v_and_b32_e32 v111, 0xffff0000, v197
	v_add_f32_e32 v116, v127, v116
	v_pk_add_f32 v[102:103], v[102:103], v[110:111]
	v_add_f32_e32 v108, v108, v116
	v_cvt_pk_bf16_f32 v106, v120, v121
	v_pk_mul_f32 v[110:111], v[102:103], v[102:103]
	v_lshlrev_b32_e32 v120, 16, v198
	v_and_b32_e32 v121, 0xffff0000, v198
	v_add_f32_e32 v108, v109, v108
	v_pk_add_f32 v[120:121], v[96:97], v[120:121]
	v_add_f32_e32 v108, v110, v108
	v_cvt_pk_bf16_f32 v107, v124, v125
	v_pk_mul_f32 v[96:97], v[120:121], v[120:121]
	v_lshlrev_b32_e32 v124, 16, v199
	v_and_b32_e32 v125, 0xffff0000, v199
	v_add_f32_e32 v108, v111, v108
	v_pk_add_f32 v[124:125], v[98:99], v[124:125]
	v_add_f32_e32 v96, v96, v108
	v_pk_mul_f32 v[98:99], v[124:125], v[124:125]
	v_add_f32_e32 v96, v97, v96
	v_add_f32_e32 v96, v98, v96
	s_waitcnt lgkmcnt(0)
	s_barrier
	v_add_f32_e32 v116, v99, v96
	v_cvt_pk_bf16_f32 v96, v100, v101
	v_cvt_pk_bf16_f32 v97, v102, v103
	v_cvt_pk_bf16_f32 v98, v120, v121
	v_cvt_pk_bf16_f32 v99, v124, v125
	ds_write_b128 v181, v[104:107]
	ds_write_b128 v181, v[96:99] offset:256
	s_add_u32 s23, s58, s36
	s_waitcnt lgkmcnt(0)
	s_barrier
	s_addc_u32 s25, s59, s37
	ds_read_b128 v[96:99], v182
	ds_read_b128 v[100:103], v182 offset:4224
	s_add_u32 s36, s23, s30
	s_addc_u32 s37, s25, s31
	v_lshl_add_u64 v[104:105], s[36:37], 0, v[152:153]
	v_lshl_add_u64 v[106:107], v[104:105], 0, v[154:155]
	s_waitcnt lgkmcnt(1)
	global_store_dwordx4 v[106:107], v[96:99], off
	s_or_b32 s36, s34, 32
	s_ashr_i32 s37, s36, 31
	v_lshl_add_u64 v[96:97], v[104:105], 0, v[156:157]
	s_waitcnt lgkmcnt(0)
	global_store_dwordx4 v[96:97], v[100:103], off
	v_lshlrev_b32_e32 v96, 16, v140
	v_and_b32_e32 v97, 0xffff0000, v140
	v_lshlrev_b32_e32 v100, 16, v142
	v_and_b32_e32 v101, 0xffff0000, v142
	v_pk_add_f32 v[100:101], v[88:89], v[100:101]
	v_lshlrev_b32_e32 v88, 16, v143
	v_and_b32_e32 v89, 0xffff0000, v143
	v_pk_add_f32 v[92:93], v[92:93], v[96:97]
	v_lshlrev_b32_e32 v98, 16, v141
	v_and_b32_e32 v99, 0xffff0000, v141
	v_pk_mul_f32 v[102:103], v[100:101], v[100:101]
	v_pk_add_f32 v[104:105], v[90:91], v[88:89]
	v_cvt_pk_bf16_f32 v90, v100, v101
	v_lshlrev_b32_e32 v100, 16, v138
	v_and_b32_e32 v101, 0xffff0000, v138
	v_pk_mul_f32 v[96:97], v[92:93], v[92:93]
	v_pk_add_f32 v[94:95], v[94:95], v[98:99]
	v_pk_add_f32 v[100:101], v[80:81], v[100:101]
	v_lshlrev_b32_e32 v80, 16, v139
	v_and_b32_e32 v81, 0xffff0000, v139
	v_pk_mul_f32 v[98:99], v[94:95], v[94:95]
	v_pk_add_f32 v[108:109], v[82:83], v[80:81]
	v_add_f32_e32 v80, v96, v97
	v_add_f32_e32 v80, v98, v80
	v_add_f32_e32 v80, v99, v80
	v_add_f32_e32 v80, v102, v80
	v_pk_mul_f32 v[106:107], v[104:105], v[104:105]
	v_cvt_pk_bf16_f32 v88, v92, v93
	v_cvt_pk_bf16_f32 v89, v94, v95
	v_lshlrev_b32_e32 v92, 16, v136
	v_and_b32_e32 v93, 0xffff0000, v136
	v_lshlrev_b32_e32 v94, 16, v137
	v_and_b32_e32 v95, 0xffff0000, v137
	v_add_f32_e32 v80, v103, v80
	v_cvt_pk_bf16_f32 v91, v104, v105
	v_pk_add_f32 v[84:85], v[84:85], v[92:93]
	v_pk_add_f32 v[86:87], v[86:87], v[94:95]
	v_add_f32_e32 v80, v106, v80
	s_waitcnt lgkmcnt(0)
	s_barrier
	v_add_f32_e32 v102, v107, v80
	v_cvt_pk_bf16_f32 v80, v84, v85
	v_cvt_pk_bf16_f32 v81, v86, v87
	v_cvt_pk_bf16_f32 v82, v100, v101
	v_cvt_pk_bf16_f32 v83, v108, v109
	s_lshl_b64 s[36:37], s[36:37], 11
	ds_write_b128 v181, v[88:91]
	ds_write_b128 v181, v[80:83] offset:256
	s_add_u32 s23, s58, s36
	s_waitcnt lgkmcnt(0)
	s_barrier
;     __device__ __forceinline__ void load(Pre& p, const pg8::Unit& u, int ai, int m, int wr, int wc, int fr, int fq) const {
;         const int row = u.pm * 256 + ai * 128 + wr * 64 + m * 16 + fr;
;         if (MODE == EM_PROJ || MODE == EM_GATES) p.rs = ((const float*)(ws + WS_RINV0))[row];
;         if (MODE == EM_RES2) p.rs = ((const float*)(ws + WS_SS1))[row];
; #pragma unroll
;         for (int bj = 0; bj < 2; ++bj) {
;             const int ct = bj * 128 + wc * 32 + fq * 8; const size_t o = (size_t)row * 1024 + u.pn * 256 + ct;
;             if (MODE == EM_MERGE) { const unsigned char* g8 = ws + WS_G8 + (size_t)row * 2048 + u.pn * 256 + ct; const u32x2 ga = *(const u32x2*)g8, gc = *(const u32x2*)(g8 + 1024);
;                 p.a[bj] = (u32x4){ga.x, ga.y, gc.x, gc.y}; p.b[bj] = *(const u32x4*)((const bf16_t*)(ws + WS_YHG) + o); }
;             if (MODE == EM_RES1) p.a[bj] = *(const u32x4*)((const bf16_t*)(ws + WS_XB) + o);
;             if (MODE == EM_RES2) { p.b[bj] = *(const u32x4*)((const bf16_t*)(ws + WS_H1B) + o); p.a[bj] = *(const u32x4*)((const bf16_t*)(ws + WS_PE) + o); }
;             if (MODE == EM_GLU && bj == 0) p.a[0] = *(const u32x4*)((const bf16_t*)(ws + WS_ZS) + (size_t)row * 512 + u.pn * 128 + wc * 32 + fq * 8);
;         }
;     }
;     __device__ __forceinline__ float compute(const Pre& p, f32x4 (&acc)[2][2][4][2], const f32x4 (&cv)[2][2], const pg8::Unit& u, int ai, int m, int wr, int wc, int fr, int fq) const {
;     ...
;             } else if (MODE == EM_RES1) {
;                 const size_t o = (size_t)row * 1024 + u.pn * 256 + ct;
;                 float w[8], xr[8]; unpack8(p.a[bj], xr);
; #pragma unroll
;                 for (int j = 0; j < 8; ++j) { w[j] = v[j] + xr[j]; ssq += w[j] * w[j]; }
;                 pk[bj] = pack8(w); (void)o;
;             } else if (MODE == EM_RES2) {
;                 const size_t o = (size_t)row * 1024 + u.pn * 256 + ct;
;                 float pe[8], h1[8]; unpack8(p.a[bj], pe); unpack8(p.b[bj], h1);
;                 float w[8];
; #pragma unroll
;                 for (int j = 0; j < 8; ++j) { w[j] = h1[j] + pe[j] * sigmoidf_(v[j] * rs); ssq += w[j] * w[j]; }
;                 acc[ai][bj][m][0] = (f32x4){w[0], w[1], w[2], w[3]}; acc[ai][bj][m][1] = (f32x4){w[4], w[5], w[6], w[7]};
;                 (void)o;
;             } else if (MODE == EM_S5A) {
	s_addc_u32 s25, s59, s37
	ds_read_b128 v[80:83], v182
	v_pk_mul_f32 v[92:93], v[84:85], v[84:85]
	v_pk_mul_f32 v[94:95], v[86:87], v[86:87]
	s_add_u32 s36, s23, s30
	ds_read_b128 v[84:87], v182 offset:4224
	s_addc_u32 s37, s25, s31
	v_lshl_add_u64 v[88:89], s[36:37], 0, v[152:153]
	v_lshl_add_u64 v[90:91], v[88:89], 0, v[154:155]
	s_waitcnt lgkmcnt(1)
	global_store_dwordx4 v[90:91], v[80:83], off
	s_or_b32 s36, s34, 48
	v_pk_mul_f32 v[104:105], v[100:101], v[100:101]
	v_lshl_add_u64 v[80:81], v[88:89], 0, v[156:157]
	s_waitcnt lgkmcnt(0)
	global_store_dwordx4 v[80:81], v[84:87], off
	v_lshlrev_b32_e32 v80, 16, v132
	v_and_b32_e32 v81, 0xffff0000, v132
	v_pk_add_f32 v[76:77], v[76:77], v[80:81]
	v_lshlrev_b32_e32 v80, 16, v133
	v_and_b32_e32 v81, 0xffff0000, v133
	v_pk_add_f32 v[78:79], v[78:79], v[80:81]
	v_lshlrev_b32_e32 v80, 16, v134
	v_and_b32_e32 v81, 0xffff0000, v134
	v_pk_add_f32 v[82:83], v[72:73], v[80:81]
	v_lshlrev_b32_e32 v80, 16, v128
	v_and_b32_e32 v81, 0xffff0000, v128
	v_pk_add_f32 v[86:87], v[68:69], v[80:81]
	v_lshlrev_b32_e32 v68, 16, v129
	v_and_b32_e32 v69, 0xffff0000, v129
	v_lshlrev_b32_e32 v72, 16, v135
	v_and_b32_e32 v73, 0xffff0000, v135
	v_pk_add_f32 v[96:97], v[70:71], v[68:69]
	v_lshlrev_b32_e32 v68, 16, v130
	v_and_b32_e32 v69, 0xffff0000, v130
	v_pk_add_f32 v[84:85], v[74:75], v[72:73]
	v_pk_add_f32 v[98:99], v[64:65], v[68:69]
	v_lshlrev_b32_e32 v64, 16, v131
	v_and_b32_e32 v65, 0xffff0000, v131
	v_cvt_pk_bf16_f32 v72, v76, v77
	v_cvt_pk_bf16_f32 v73, v78, v79
	v_cvt_pk_bf16_f32 v74, v82, v83
	v_cvt_pk_bf16_f32 v75, v84, v85
	v_pk_add_f32 v[100:101], v[66:67], v[64:65]
	s_ashr_i32 s37, s36, 31
	s_waitcnt lgkmcnt(0)
	s_barrier
	v_cvt_pk_bf16_f32 v64, v86, v87
	v_cvt_pk_bf16_f32 v65, v96, v97
	v_cvt_pk_bf16_f32 v66, v98, v99
	v_cvt_pk_bf16_f32 v67, v100, v101
	s_lshl_b64 s[36:37], s[36:37], 11
	ds_write_b128 v181, v[72:75]
	ds_write_b128 v181, v[64:67] offset:256
	s_add_u32 s23, s58, s36
	s_waitcnt lgkmcnt(0)
	s_barrier
	s_addc_u32 s25, s59, s37
	ds_read_b128 v[64:67], v182
	ds_read_b128 v[68:71], v182 offset:4224
	s_add_u32 s36, s23, s30
	s_addc_u32 s37, s25, s31
	v_lshl_add_u64 v[72:73], s[36:37], 0, v[152:153]
	v_lshl_add_u64 v[74:75], v[72:73], 0, v[154:155]
	v_add_u32_e32 v80, 0x80, v170
	s_waitcnt lgkmcnt(1)
	global_store_dwordx4 v[74:75], v[64:67], off
	v_ashrrev_i32_e32 v81, 31, v80
	v_xor_b32_e32 v113, 32, v183
	v_lshl_add_u64 v[64:65], v[72:73], 0, v[156:157]
	s_waitcnt lgkmcnt(0)
	global_store_dwordx4 v[64:65], v[68:71], off
	v_lshlrev_b64 v[64:65], 11, v[80:81]
	s_waitcnt lgkmcnt(0)
	s_barrier
	v_lshl_add_u64 v[66:67], v[172:173], 0, v[64:65]
	v_mov_b64_e32 v[88:89], v[208:209]
	v_mov_b64_e32 v[90:91], v[210:211]
	v_add_f32_e32 v66, v92, v102
	v_add_f32_e32 v66, v93, v66
	v_add_f32_e32 v66, v94, v66
	v_cmp_lt_i32_e32 vcc, v113, v115
	v_add_f32_e32 v66, v95, v66
	v_lshl_add_u64 v[64:65], v[174:175], 0, v[64:65]
	v_cndmask_b32_e32 v113, v183, v113, vcc
	v_add_f32_e32 v66, v104, v66
	v_add_co_u32_e32 v64, vcc, s62, v64
	v_pk_mul_f32 v[110:111], v[108:109], v[108:109]
	v_add_f32_e32 v66, v105, v66
	v_addc_co_u32_e32 v65, vcc, 0, v65, vcc
	v_add_f32_e32 v66, v110, v66
	v_mov_b64_e32 v[92:93], v[212:213]
	v_mov_b64_e32 v[94:95], v[214:215]
	v_add_f32_e32 v102, v111, v66
	v_pk_mul_f32 v[66:67], v[76:77], v[76:77]
	v_pk_mul_f32 v[68:69], v[78:79], v[78:79]
	v_add_f32_e32 v66, v66, v67
	v_add_f32_e32 v66, v68, v66
	v_pk_mul_f32 v[70:71], v[82:83], v[82:83]
	v_add_f32_e32 v66, v69, v66
	v_add_f32_e32 v66, v70, v66
	v_pk_mul_f32 v[72:73], v[84:85], v[84:85]
	v_add_f32_e32 v66, v71, v66
	v_add_f32_e32 v66, v72, v66
	v_pk_mul_f32 v[74:75], v[86:87], v[86:87]
	v_add_f32_e32 v66, v73, v66
	v_add_f32_e32 v66, v74, v66
	v_pk_mul_f32 v[64:65], v[96:97], v[96:97]
	v_add_f32_e32 v66, v75, v66
	v_add_f32_e32 v64, v64, v66
	v_pk_mul_f32 v[76:77], v[98:99], v[98:99]
	v_add_f32_e32 v64, v65, v64
	v_add_f32_e32 v64, v76, v64
	v_pk_mul_f32 v[78:79], v[100:101], v[100:101]
	v_add_f32_e32 v64, v77, v64
	v_add_f32_e32 v64, v78, v64
	v_add_f32_e32 v64, v79, v64
	ds_bpermute_b32 v65, v114, v64
	ds_bpermute_b32 v103, v114, v102
	s_add_i32 s36, s34, 0x80
	s_ashr_i32 s37, s36, 31
	s_lshl_b64 s[36:37], s[36:37], 11
	s_waitcnt lgkmcnt(1)
	v_add_f32_e32 v86, v64, v65
	v_add_u32_e32 v64, 0x90, v170
	v_ashrrev_i32_e32 v65, 31, v64
	v_lshlrev_b64 v[64:65], 11, v[64:65]
	v_lshl_add_u64 v[66:67], v[172:173], 0, v[64:65]
	v_lshl_add_u64 v[64:65], v[174:175], 0, v[64:65]
	v_add_co_u32_e32 v64, vcc, s62, v64
	s_waitcnt lgkmcnt(0)
	v_add_f32_e32 v84, v102, v103
	v_addc_co_u32_e32 v65, vcc, 0, v65, vcc
	v_mov_b64_e32 v[96:97], v[216:217]
	v_mov_b64_e32 v[98:99], v[218:219]
	v_mov_b64_e32 v[100:101], v[220:221]
	v_mov_b64_e32 v[102:103], v[222:223]
	v_add_u32_e32 v64, 0xa0, v170
	v_ashrrev_i32_e32 v65, 31, v64
	v_lshlrev_b64 v[64:65], 11, v[64:65]
	v_lshl_add_u64 v[66:67], v[172:173], 0, v[64:65]
	v_lshl_add_u64 v[64:65], v[174:175], 0, v[64:65]
	v_add_co_u32_e32 v64, vcc, s62, v64
	s_add_u32 s23, s58, s36
	s_nop 0
	v_addc_co_u32_e32 v65, vcc, 0, v65, vcc
	v_mov_b64_e32 v[76:77], v[224:225]
	v_mov_b64_e32 v[78:79], v[226:227]
	v_mov_b64_e32 v[72:73], v[228:229]
	v_mov_b64_e32 v[74:75], v[230:231]
	v_add_u32_e32 v64, 0xb0, v170
	v_ashrrev_i32_e32 v65, 31, v64
	v_lshlrev_b64 v[64:65], 11, v[64:65]
	v_lshl_add_u64 v[66:67], v[172:173], 0, v[64:65]
	v_lshl_add_u64 v[64:65], v[174:175], 0, v[64:65]
	v_add_co_u32_e32 v64, vcc, s62, v64
	s_addc_u32 s25, s59, s37
	s_nop 0
	v_addc_co_u32_e32 v65, vcc, 0, v65, vcc
	v_mov_b64_e32 v[68:69], v[232:233]
	v_mov_b64_e32 v[70:71], v[234:235]
	s_nop 0
	v_mov_b64_e32 v[64:65], v[236:237]
	v_mov_b64_e32 v[66:67], v[238:239]
	s_waitcnt vmcnt(7)
;     __device__ __forceinline__ void stage512(const u32x4 a, const u32x4 b, unsigned char* g0, size_t ldb, int wr, int wc, int fr, int fq) const {
;         LAS unsigned char* sb = lds + LDS_STG + wr * 8448;
;     __device__ __forceinline__ float compute(const Pre& p, f32x4 (&acc)[2][2][4][2], const f32x4 (&cv)[2][2], const pg8::Unit& u, int ai, int m, int wr, int wc, int fr, int fq) const {
;     ...
;             } else if (MODE == EM_RES1) {
;                 const size_t o = (size_t)row * 1024 + u.pn * 256 + ct;
;                 float w[8], xr[8]; unpack8(p.a[bj], xr);
; #pragma unroll
;                 for (int j = 0; j < 8; ++j) { w[j] = v[j] + xr[j]; ssq += w[j] * w[j]; }
;                 pk[bj] = pack8(w); (void)o;
;             } else if (MODE == EM_RES2) {
;                 const size_t o = (size_t)row * 1024 + u.pn * 256 + ct;
;                 float pe[8], h1[8]; unpack8(p.a[bj], pe); unpack8(p.b[bj], h1);
;                 float w[8];
; #pragma unroll
;                 for (int j = 0; j < 8; ++j) { w[j] = h1[j] + pe[j] * sigmoidf_(v[j] * rs); ssq += w[j] * w[j]; }
;                 acc[ai][bj][m][0] = (f32x4){w[0], w[1], w[2], w[3]}; acc[ai][bj][m][1] = (f32x4){w[4], w[5], w[6], w[7]};
;                 (void)o;
;             } else if (MODE == EM_S5A) {
;                 float* e = (float*)(ws + WS_E) + (size_t)row * 128 + ct;
;                 *(f32x4*)e = (f32x4){v[0], v[1], v[2], v[3]}; *(f32x4*)(e + 4) = (f32x4){v[4], v[5], v[6], v[7]};
;             } else if (MODE == EM_S5C) {
;                 const int g = u.pn, cr = row - g * 2048; const int tok = cr * 16 + (ct >> 4);
;                 float w[8];
; #pragma unroll
;                 for (int j = 0; j < 8; ++j) w[j] = gelu_tanh(v[j]);
;                 *(u32x4*)((bf16_t*)(ws + WS_YSA) + (size_t)tok * 512 + g * 16 + (ct & 15)) = pack8(w);
;             }
;         }
;         if (MODE == EM_PLAIN) stage512(pk[0], pk[1], (unsigned char*)O + (trow * ldc + u.pn * 256) * 2, (size_t)ldc * 2, wr, wc, fr, fq);
;         if (MODE == EM_MERGE) stage512(pk[0], pk[1], ws + WS_MRG + (trow * 1024 + u.pn * 256) * 2, 2048, wr, wc, fr, fq);
;         if (MODE == EM_RES1) stage512(pk[0], pk[1], ws + WS_H1B + (trow * 1024 + u.pn * 256) * 2, 2048, wr, wc, fr, fq);
;         if (MODE == EM_RES1 || MODE == EM_RES2) { ssq += __shfl_xor(ssq, 16); ssq += __shfl_xor(ssq, 32); }
	v_lshlrev_b32_e32 v104, 16, v88
	v_and_b32_e32 v105, 0xffff0000, v88
	v_lshlrev_b32_e32 v106, 16, v90
	v_and_b32_e32 v107, 0xffff0000, v90
	v_pk_add_f32 v[60:61], v[60:61], v[104:105]
	v_lshlrev_b32_e32 v88, 16, v89
	v_and_b32_e32 v89, 0xffff0000, v89
	v_pk_add_f32 v[106:107], v[56:57], v[106:107]
	v_lshlrev_b32_e32 v56, 16, v91
	v_and_b32_e32 v57, 0xffff0000, v91
	v_pk_mul_f32 v[104:105], v[60:61], v[60:61]
	v_pk_add_f32 v[62:63], v[62:63], v[88:89]
	v_pk_add_f32 v[90:91], v[58:59], v[56:57]
	v_pk_mul_f32 v[88:89], v[62:63], v[62:63]
	v_pk_mul_f32 v[110:111], v[90:91], v[90:91]
	v_cvt_pk_bf16_f32 v59, v90, v91
	s_waitcnt vmcnt(6)
	v_lshlrev_b32_e32 v90, 16, v94
	v_and_b32_e32 v91, 0xffff0000, v94
	v_add_f32_e32 v94, v104, v105
	v_add_f32_e32 v88, v88, v94
	v_pk_mul_f32 v[108:109], v[106:107], v[106:107]
	v_add_f32_e32 v88, v89, v88
	v_add_f32_e32 v88, v108, v88
	v_cvt_pk_bf16_f32 v56, v60, v61
	v_lshlrev_b32_e32 v60, 16, v92
	v_and_b32_e32 v61, 0xffff0000, v92
	v_add_f32_e32 v88, v109, v88
	v_pk_add_f32 v[52:53], v[52:53], v[60:61]
	v_add_f32_e32 v88, v110, v88
	v_cvt_pk_bf16_f32 v57, v62, v63
	v_pk_mul_f32 v[60:61], v[52:53], v[52:53]
	v_lshlrev_b32_e32 v62, 16, v93
	v_and_b32_e32 v63, 0xffff0000, v93
	v_add_f32_e32 v88, v111, v88
	v_pk_add_f32 v[54:55], v[54:55], v[62:63]
	v_add_f32_e32 v60, v60, v88
	v_pk_mul_f32 v[62:63], v[54:55], v[54:55]
	v_add_f32_e32 v60, v61, v60
	v_pk_add_f32 v[90:91], v[48:49], v[90:91]
	v_add_f32_e32 v60, v62, v60
	v_pk_mul_f32 v[48:49], v[90:91], v[90:91]
	v_lshlrev_b32_e32 v92, 16, v95
	v_and_b32_e32 v93, 0xffff0000, v95
	v_add_f32_e32 v60, v63, v60
	v_pk_add_f32 v[92:93], v[50:51], v[92:93]
	v_add_f32_e32 v48, v48, v60
	v_pk_mul_f32 v[50:51], v[92:93], v[92:93]
	v_add_f32_e32 v48, v49, v48
	v_cvt_pk_bf16_f32 v58, v106, v107
	v_add_f32_e32 v48, v50, v48
	v_add_f32_e32 v60, v51, v48
	v_cvt_pk_bf16_f32 v48, v52, v53
	v_cvt_pk_bf16_f32 v49, v54, v55
	v_cvt_pk_bf16_f32 v50, v90, v91
	v_cvt_pk_bf16_f32 v51, v92, v93
	ds_write_b128 v181, v[56:59]
	ds_write_b128 v181, v[48:51] offset:256
	s_waitcnt lgkmcnt(0)
	s_barrier
	ds_read_b128 v[48:51], v182
	ds_read_b128 v[52:55], v182 offset:4224
	s_add_u32 s36, s23, s30
	s_addc_u32 s37, s25, s31
	v_lshl_add_u64 v[56:57], s[36:37], 0, v[152:153]
	v_lshl_add_u64 v[58:59], v[56:57], 0, v[154:155]
	s_waitcnt lgkmcnt(1)
	global_store_dwordx4 v[58:59], v[48:51], off
	ds_bpermute_b32 v50, v114, v60
	s_add_i32 s36, s34, 0x90
	v_lshl_add_u64 v[48:49], v[56:57], 0, v[156:157]
	s_waitcnt lgkmcnt(1)
	global_store_dwordx4 v[48:49], v[52:55], off
	s_waitcnt vmcnt(7)
	v_and_b32_e32 v51, 0xffff0000, v96
	s_waitcnt lgkmcnt(0)
	v_add_f32_e32 v48, v60, v50
	v_lshlrev_b32_e32 v50, 16, v96
	v_pk_add_f32 v[44:45], v[44:45], v[50:51]
	v_lshlrev_b32_e32 v52, 16, v97
	v_and_b32_e32 v53, 0xffff0000, v97
	v_pk_mul_f32 v[50:51], v[44:45], v[44:45]
	v_pk_add_f32 v[46:47], v[46:47], v[52:53]
	v_lshlrev_b32_e32 v54, 16, v98
	v_pk_mul_f32 v[52:53], v[46:47], v[46:47]
	v_and_b32_e32 v55, 0xffff0000, v98
	v_add_f32_e32 v50, v50, v51
	v_pk_add_f32 v[54:55], v[40:41], v[54:55]
	v_add_f32_e32 v50, v52, v50
	v_pk_mul_f32 v[56:57], v[54:55], v[54:55]
	v_lshlrev_b32_e32 v40, 16, v99
	v_and_b32_e32 v41, 0xffff0000, v99
	v_add_f32_e32 v50, v53, v50
	v_pk_add_f32 v[58:59], v[42:43], v[40:41]
	v_add_f32_e32 v50, v56, v50
	v_pk_mul_f32 v[60:61], v[58:59], v[58:59]
	v_cvt_pk_bf16_f32 v40, v44, v45
	s_waitcnt vmcnt(6)
	v_lshlrev_b32_e32 v44, 16, v100
	v_and_b32_e32 v45, 0xffff0000, v100
	v_add_f32_e32 v50, v57, v50
	v_pk_add_f32 v[36:37], v[36:37], v[44:45]
	v_add_f32_e32 v50, v60, v50
	v_cvt_pk_bf16_f32 v41, v46, v47
	v_pk_mul_f32 v[44:45], v[36:37], v[36:37]
	v_lshlrev_b32_e32 v46, 16, v101
	v_and_b32_e32 v47, 0xffff0000, v101
	v_add_f32_e32 v50, v61, v50
	v_pk_add_f32 v[38:39], v[38:39], v[46:47]
	v_add_f32_e32 v44, v44, v50
	v_cvt_pk_bf16_f32 v42, v54, v55
	v_pk_mul_f32 v[46:47], v[38:39], v[38:39]
	v_lshlrev_b32_e32 v54, 16, v102
	v_and_b32_e32 v55, 0xffff0000, v102
	v_add_f32_e32 v44, v45, v44
	v_pk_add_f32 v[54:55], v[32:33], v[54:55]
	v_add_f32_e32 v44, v46, v44
	v_cvt_pk_bf16_f32 v43, v58, v59
	v_pk_mul_f32 v[32:33], v[54:55], v[54:55]
	v_lshlrev_b32_e32 v58, 16, v103
	v_and_b32_e32 v59, 0xffff0000, v103
	v_add_f32_e32 v44, v47, v44
	v_pk_add_f32 v[58:59], v[34:35], v[58:59]
	v_add_f32_e32 v32, v32, v44
	v_pk_mul_f32 v[34:35], v[58:59], v[58:59]
	v_add_f32_e32 v32, v33, v32
	v_add_f32_e32 v32, v34, v32
	s_ashr_i32 s37, s36, 31
	s_waitcnt lgkmcnt(0)
	s_barrier
	v_add_f32_e32 v44, v35, v32
	v_cvt_pk_bf16_f32 v32, v36, v37
	v_cvt_pk_bf16_f32 v33, v38, v39
	v_cvt_pk_bf16_f32 v34, v54, v55
	v_cvt_pk_bf16_f32 v35, v58, v59
	s_lshl_b64 s[36:37], s[36:37], 11
	ds_write_b128 v181, v[40:43]
	ds_write_b128 v181, v[32:35] offset:256
	s_add_u32 s23, s58, s36
	s_waitcnt lgkmcnt(0)
	s_barrier
;     __device__ __forceinline__ void stage512(const u32x4 a, const u32x4 b, unsigned char* g0, size_t ldb, int wr, int wc, int fr, int fq) const {
;         LAS unsigned char* sb = lds + LDS_STG + wr * 8448;
;     __device__ __forceinline__ float compute(const Pre& p, f32x4 (&acc)[2][2][4][2], const f32x4 (&cv)[2][2], const pg8::Unit& u, int ai, int m, int wr, int wc, int fr, int fq) const {
;     ...
;             } else if (MODE == EM_RES1) {
;                 const size_t o = (size_t)row * 1024 + u.pn * 256 + ct;
;                 float w[8], xr[8]; unpack8(p.a[bj], xr);
; #pragma unroll
;                 for (int j = 0; j < 8; ++j) { w[j] = v[j] + xr[j]; ssq += w[j] * w[j]; }
;                 pk[bj] = pack8(w); (void)o;
;             } else if (MODE == EM_RES2) {
;                 const size_t o = (size_t)row * 1024 + u.pn * 256 + ct;
;                 float pe[8], h1[8]; unpack8(p.a[bj], pe); unpack8(p.b[bj], h1);
;                 float w[8];
; #pragma unroll
;                 for (int j = 0; j < 8; ++j) { w[j] = h1[j] + pe[j] * sigmoidf_(v[j] * rs); ssq += w[j] * w[j]; }
;                 acc[ai][bj][m][0] = (f32x4){w[0], w[1], w[2], w[3]}; acc[ai][bj][m][1] = (f32x4){w[4], w[5], w[6], w[7]};
;                 (void)o;
;             } else if (MODE == EM_S5A) {
;                 float* e = (float*)(ws + WS_E) + (size_t)row * 128 + ct;
;                 *(f32x4*)e = (f32x4){v[0], v[1], v[2], v[3]}; *(f32x4*)(e + 4) = (f32x4){v[4], v[5], v[6], v[7]};
;             } else if (MODE == EM_S5C) {
;                 const int g = u.pn, cr = row - g * 2048; const int tok = cr * 16 + (ct >> 4);
;                 float w[8];
; #pragma unroll
;                 for (int j = 0; j < 8; ++j) w[j] = gelu_tanh(v[j]);
;                 *(u32x4*)((bf16_t*)(ws + WS_YSA) + (size_t)tok * 512 + g * 16 + (ct & 15)) = pack8(w);
;             }
;         }
;         if (MODE == EM_PLAIN) stage512(pk[0], pk[1], (unsigned char*)O + (trow * ldc + u.pn * 256) * 2, (size_t)ldc * 2, wr, wc, fr, fq);
;         if (MODE == EM_MERGE) stage512(pk[0], pk[1], ws + WS_MRG + (trow * 1024 + u.pn * 256) * 2, 2048, wr, wc, fr, fq);
;         if (MODE == EM_RES1) stage512(pk[0], pk[1], ws + WS_H1B + (trow * 1024 + u.pn * 256) * 2, 2048, wr, wc, fr, fq);
;         if (MODE == EM_RES1 || MODE == EM_RES2) { ssq += __shfl_xor(ssq, 16); ssq += __shfl_xor(ssq, 32); }
	s_addc_u32 s25, s59, s37
	ds_read_b128 v[32:35], v182
	ds_read_b128 v[36:39], v182 offset:4224
	s_add_u32 s36, s23, s30
	s_addc_u32 s37, s25, s31
	v_lshl_add_u64 v[40:41], s[36:37], 0, v[152:153]
	v_lshl_add_u64 v[42:43], v[40:41], 0, v[154:155]
	s_waitcnt lgkmcnt(1)
	global_store_dwordx4 v[42:43], v[32:35], off
	ds_bpermute_b32 v34, v114, v44
	s_add_i32 s36, s34, 0xa0
	v_lshl_add_u64 v[32:33], v[40:41], 0, v[156:157]
	s_waitcnt lgkmcnt(1)
	global_store_dwordx4 v[32:33], v[36:39], off
	s_waitcnt vmcnt(7)
	v_and_b32_e32 v35, 0xffff0000, v76
	s_waitcnt lgkmcnt(0)
	v_add_f32_e32 v32, v44, v34
	v_lshlrev_b32_e32 v34, 16, v76
	v_pk_add_f32 v[28:29], v[28:29], v[34:35]
	v_lshlrev_b32_e32 v36, 16, v77
	v_and_b32_e32 v37, 0xffff0000, v77
	v_pk_mul_f32 v[34:35], v[28:29], v[28:29]
	v_pk_add_f32 v[30:31], v[30:31], v[36:37]
	v_lshlrev_b32_e32 v38, 16, v78
	v_pk_mul_f32 v[36:37], v[30:31], v[30:31]
	v_and_b32_e32 v39, 0xffff0000, v78
	v_add_f32_e32 v34, v34, v35
	v_pk_add_f32 v[38:39], v[24:25], v[38:39]
	v_add_f32_e32 v34, v36, v34
	v_pk_mul_f32 v[40:41], v[38:39], v[38:39]
	v_lshlrev_b32_e32 v24, 16, v79
	v_and_b32_e32 v25, 0xffff0000, v79
	v_add_f32_e32 v34, v37, v34
	v_pk_add_f32 v[42:43], v[26:27], v[24:25]
	v_add_f32_e32 v34, v40, v34
	v_pk_mul_f32 v[44:45], v[42:43], v[42:43]
	v_cvt_pk_bf16_f32 v24, v28, v29
	s_waitcnt vmcnt(6)
	v_lshlrev_b32_e32 v28, 16, v72
	v_and_b32_e32 v29, 0xffff0000, v72
	v_add_f32_e32 v34, v41, v34
	v_pk_add_f32 v[20:21], v[20:21], v[28:29]
	v_add_f32_e32 v34, v44, v34
	v_cvt_pk_bf16_f32 v25, v30, v31
	v_pk_mul_f32 v[28:29], v[20:21], v[20:21]
	v_lshlrev_b32_e32 v30, 16, v73
	v_and_b32_e32 v31, 0xffff0000, v73
	v_add_f32_e32 v34, v45, v34
	v_pk_add_f32 v[22:23], v[22:23], v[30:31]
	v_add_f32_e32 v28, v28, v34
	v_cvt_pk_bf16_f32 v26, v38, v39
	v_pk_mul_f32 v[30:31], v[22:23], v[22:23]
	v_lshlrev_b32_e32 v38, 16, v74
	v_and_b32_e32 v39, 0xffff0000, v74
	v_add_f32_e32 v28, v29, v28
	v_pk_add_f32 v[38:39], v[16:17], v[38:39]
	v_add_f32_e32 v28, v30, v28
	v_cvt_pk_bf16_f32 v27, v42, v43
	v_pk_mul_f32 v[16:17], v[38:39], v[38:39]
	v_lshlrev_b32_e32 v42, 16, v75
	v_and_b32_e32 v43, 0xffff0000, v75
	v_add_f32_e32 v28, v31, v28
	v_pk_add_f32 v[42:43], v[18:19], v[42:43]
	v_add_f32_e32 v16, v16, v28
	v_pk_mul_f32 v[18:19], v[42:43], v[42:43]
	v_add_f32_e32 v16, v17, v16
	v_add_f32_e32 v16, v18, v16
	s_ashr_i32 s37, s36, 31
	s_waitcnt lgkmcnt(0)
	s_barrier
	v_add_f32_e32 v28, v19, v16
	v_cvt_pk_bf16_f32 v16, v20, v21
	v_cvt_pk_bf16_f32 v17, v22, v23
	v_cvt_pk_bf16_f32 v18, v38, v39
	v_cvt_pk_bf16_f32 v19, v42, v43
	s_lshl_b64 s[36:37], s[36:37], 11
	ds_write_b128 v181, v[24:27]
	ds_write_b128 v181, v[16:19] offset:256
	s_add_u32 s23, s58, s36
	s_waitcnt lgkmcnt(0)
	s_barrier
;     __device__ __forceinline__ float compute(const Pre& p, f32x4 (&acc)[2][2][4][2], const f32x4 (&cv)[2][2], const pg8::Unit& u, int ai, int m, int wr, int wc, int fr, int fq) const {
;     ...
;             } else if (MODE == EM_RES1) {
;                 const size_t o = (size_t)row * 1024 + u.pn * 256 + ct;
;                 float w[8], xr[8]; unpack8(p.a[bj], xr);
; #pragma unroll
;                 for (int j = 0; j < 8; ++j) { w[j] = v[j] + xr[j]; ssq += w[j] * w[j]; }
;                 pk[bj] = pack8(w); (void)o;
;             } else if (MODE == EM_RES2) {
;                 const size_t o = (size_t)row * 1024 + u.pn * 256 + ct;
;                 float pe[8], h1[8]; unpack8(p.a[bj], pe); unpack8(p.b[bj], h1);
;                 float w[8];
; #pragma unroll
;                 for (int j = 0; j < 8; ++j) { w[j] = h1[j] + pe[j] * sigmoidf_(v[j] * rs); ssq += w[j] * w[j]; }
;                 acc[ai][bj][m][0] = (f32x4){w[0], w[1], w[2], w[3]}; acc[ai][bj][m][1] = (f32x4){w[4], w[5], w[6], w[7]};
;                 (void)o;
;             } else if (MODE == EM_S5A) {
;                 float* e = (float*)(ws + WS_E) + (size_t)row * 128 + ct;
;                 *(f32x4*)e = (f32x4){v[0], v[1], v[2], v[3]}; *(f32x4*)(e + 4) = (f32x4){v[4], v[5], v[6], v[7]};
;             } else if (MODE == EM_S5C) {
;                 const int g = u.pn, cr = row - g * 2048; const int tok = cr * 16 + (ct >> 4);
;                 float w[8];
; #pragma unroll
;                 for (int j = 0; j < 8; ++j) w[j] = gelu_tanh(v[j]);
;                 *(u32x4*)((bf16_t*)(ws + WS_YSA) + (size_t)tok * 512 + g * 16 + (ct & 15)) = pack8(w);
;             }
;         }
;         if (MODE == EM_PLAIN) stage512(pk[0], pk[1], (unsigned char*)O + (trow * ldc + u.pn * 256) * 2, (size_t)ldc * 2, wr, wc, fr, fq);
;         if (MODE == EM_MERGE) stage512(pk[0], pk[1], ws + WS_MRG + (trow * 1024 + u.pn * 256) * 2, 2048, wr, wc, fr, fq);
;         if (MODE == EM_RES1) stage512(pk[0], pk[1], ws + WS_H1B + (trow * 1024 + u.pn * 256) * 2, 2048, wr, wc, fr, fq);
;         if (MODE == EM_RES1 || MODE == EM_RES2) { ssq += __shfl_xor(ssq, 16); ssq += __shfl_xor(ssq, 32); }
;     __device__ __forceinline__ void operator()(f32x4 (&acc)[2][2][4][2], const pg8::Unit& u, int wr, int wc, int fr, int fq) const {
;     ...
;         if (MODE == EM_RES1 || MODE == EM_RES2) {
; #pragma unroll
	s_addc_u32 s25, s59, s37
	ds_read_b128 v[16:19], v182
	ds_read_b128 v[20:23], v182 offset:4224
	s_add_u32 s36, s23, s30
	s_addc_u32 s37, s25, s31
	v_lshl_add_u64 v[24:25], s[36:37], 0, v[152:153]
	v_lshl_add_u64 v[26:27], v[24:25], 0, v[154:155]
	s_waitcnt lgkmcnt(1)
	global_store_dwordx4 v[26:27], v[16:19], off
	ds_bpermute_b32 v18, v114, v28
	s_addk_i32 s34, 0xb0
	v_lshl_add_u64 v[16:17], v[24:25], 0, v[156:157]
	s_waitcnt lgkmcnt(1)
	global_store_dwordx4 v[16:17], v[20:23], off
	s_waitcnt vmcnt(7)
	v_and_b32_e32 v19, 0xffff0000, v68
	s_waitcnt lgkmcnt(0)
	v_add_f32_e32 v16, v28, v18
	v_lshlrev_b32_e32 v18, 16, v68
	v_pk_add_f32 v[12:13], v[12:13], v[18:19]
	v_lshlrev_b32_e32 v20, 16, v69
	v_and_b32_e32 v21, 0xffff0000, v69
	v_pk_mul_f32 v[18:19], v[12:13], v[12:13]
	v_pk_add_f32 v[14:15], v[14:15], v[20:21]
	v_lshlrev_b32_e32 v22, 16, v70
	v_pk_mul_f32 v[20:21], v[14:15], v[14:15]
	v_and_b32_e32 v23, 0xffff0000, v70
	v_add_f32_e32 v18, v18, v19
	v_pk_add_f32 v[22:23], v[8:9], v[22:23]
	v_add_f32_e32 v18, v20, v18
	v_pk_mul_f32 v[24:25], v[22:23], v[22:23]
	v_lshlrev_b32_e32 v8, 16, v71
	v_and_b32_e32 v9, 0xffff0000, v71
	v_add_f32_e32 v18, v21, v18
	v_pk_add_f32 v[26:27], v[10:11], v[8:9]
	v_add_f32_e32 v18, v24, v18
	v_pk_mul_f32 v[28:29], v[26:27], v[26:27]
	v_cvt_pk_bf16_f32 v8, v12, v13
	s_waitcnt vmcnt(6)
	v_lshlrev_b32_e32 v12, 16, v64
	v_and_b32_e32 v13, 0xffff0000, v64
	v_add_f32_e32 v18, v25, v18
	v_pk_add_f32 v[4:5], v[4:5], v[12:13]
	v_add_f32_e32 v18, v28, v18
	v_cvt_pk_bf16_f32 v9, v14, v15
	v_pk_mul_f32 v[12:13], v[4:5], v[4:5]
	v_lshlrev_b32_e32 v14, 16, v65
	v_and_b32_e32 v15, 0xffff0000, v65
	v_add_f32_e32 v18, v29, v18
	v_pk_add_f32 v[6:7], v[6:7], v[14:15]
	v_add_f32_e32 v12, v12, v18
	v_cvt_pk_bf16_f32 v10, v22, v23
	v_pk_mul_f32 v[14:15], v[6:7], v[6:7]
	v_lshlrev_b32_e32 v22, 16, v66
	v_and_b32_e32 v23, 0xffff0000, v66
	v_add_f32_e32 v12, v13, v12
	v_pk_add_f32 v[22:23], v[0:1], v[22:23]
	v_add_f32_e32 v12, v14, v12
	v_cvt_pk_bf16_f32 v11, v26, v27
	v_pk_mul_f32 v[0:1], v[22:23], v[22:23]
	v_lshlrev_b32_e32 v26, 16, v67
	v_and_b32_e32 v27, 0xffff0000, v67
	v_add_f32_e32 v12, v15, v12
	v_pk_add_f32 v[26:27], v[2:3], v[26:27]
	v_add_f32_e32 v0, v0, v12
	v_pk_mul_f32 v[2:3], v[26:27], v[26:27]
	v_add_f32_e32 v0, v1, v0
	v_add_f32_e32 v0, v2, v0
	s_ashr_i32 s35, s34, 31
	s_waitcnt lgkmcnt(0)
	s_barrier
	v_add_f32_e32 v12, v3, v0
	v_cvt_pk_bf16_f32 v0, v4, v5
	v_cvt_pk_bf16_f32 v1, v6, v7
	v_cvt_pk_bf16_f32 v2, v22, v23
	v_cvt_pk_bf16_f32 v3, v26, v27
	s_lshl_b64 s[34:35], s[34:35], 11
	ds_write_b128 v181, v[8:11]
	ds_write_b128 v181, v[0:3] offset:256
	s_add_u32 s23, s58, s34
	s_waitcnt lgkmcnt(0)
	s_barrier
	s_addc_u32 s25, s59, s35
	ds_read_b128 v[0:3], v182
	ds_read_b128 v[4:7], v182 offset:4224
	s_add_u32 s30, s23, s30
	s_addc_u32 s31, s25, s31
	v_lshl_add_u64 v[8:9], s[30:31], 0, v[152:153]
	v_lshl_add_u64 v[10:11], v[8:9], 0, v[154:155]
	ds_bpermute_b32 v117, v114, v116
	s_waitcnt lgkmcnt(2)
	global_store_dwordx4 v[10:11], v[0:3], off
	ds_bpermute_b32 v2, v114, v12
	v_lshlrev_b32_e32 v115, 2, v113
	v_lshl_add_u64 v[0:1], v[8:9], 0, v[156:157]
	s_waitcnt lgkmcnt(1)
	v_add_f32_e32 v82, v116, v117
	global_store_dwordx4 v[0:1], v[4:7], off
	s_waitcnt lgkmcnt(0)
	v_add_f32_e32 v0, v12, v2
	ds_bpermute_b32 v113, v115, v112
	ds_bpermute_b32 v83, v115, v82
	ds_bpermute_b32 v85, v115, v84
	ds_bpermute_b32 v87, v115, v86
	ds_bpermute_b32 v49, v115, v48
	ds_bpermute_b32 v33, v115, v32
	ds_bpermute_b32 v17, v115, v16
	ds_bpermute_b32 v1, v115, v0
	s_waitcnt lgkmcnt(0)
	s_barrier
	s_and_saveexec_b64 s[30:31], s[4:5]
	v_readlane_b32 s66, v255, 7
	v_readlane_b32 s67, v255, 8
	s_cbranch_execz .LBB0_1256
	s_waitcnt lgkmcnt(0)
	v_add_f32_e32 v4, v0, v1
	v_lshlrev_b64 v[0:1], 2, v[170:171]
	v_lshl_add_u64 v[2:3], s[20:21], 0, v[0:1]
	v_lshl_add_u64 v[0:1], s[92:93], 0, v[0:1]
	v_add_f32_e32 v10, v112, v113
	v_add_co_u32_e32 v0, vcc, 0x1f440000, v0
	v_add_f32_e32 v11, v82, v83
	global_atomic_add_f32 v[2:3], v10, off
	v_addc_co_u32_e32 v1, vcc, 0, v1, vcc
	v_add_f32_e32 v8, v86, v87
	v_add_f32_e32 v9, v84, v85
	global_atomic_add_f32 v[0:1], v11, off offset:64
	global_atomic_add_f32 v[0:1], v9, off offset:128
	global_atomic_add_f32 v[0:1], v8, off offset:192
	v_lshlrev_b64 v[0:1], 2, v[80:81]
	v_lshl_add_u64 v[2:3], s[20:21], 0, v[0:1]
	v_lshl_add_u64 v[0:1], s[92:93], 0, v[0:1]
	v_add_f32_e32 v7, v48, v49
	v_add_co_u32_e32 v0, vcc, 0x1f440000, v0
	v_add_f32_e32 v6, v32, v33
	global_atomic_add_f32 v[2:3], v7, off
	v_addc_co_u32_e32 v1, vcc, 0, v1, vcc
	v_add_f32_e32 v5, v16, v17
	global_atomic_add_f32 v[0:1], v6, off offset:64
	global_atomic_add_f32 v[0:1], v5, off offset:128
	global_atomic_add_f32 v[0:1], v4, off offset:192
